# context-row 256-point DFT computed as a two-stage 16x16 FFT in LDS (f32, same twiddle table) instead of the direct O(N^2) sum
# speedup vs baseline: 1.0556x; 1.0016x over previous
.LBB0_447:
	s_waitcnt lgkmcnt(0)
	s_load_dwordx2 s[6:7], s[82:83], 0xb0
	s_waitcnt vmcnt(6)
	v_cndmask_b32_e64 v0, 0, 1, s[4:5]
	v_cmp_ne_u32_e64 s[8:9], 1, v0
	s_andn2_b64 vcc, exec, s[4:5]
	s_nop 0
	v_writelane_b32 v254, s8, 4
	s_nop 1
	v_writelane_b32 v254, s9, 5
	s_cbranch_vccnz .LBB0_454
	v_mbcnt_lo_u32_b32 v0, -1, 0
	v_mbcnt_hi_u32_b32 v0, -1, v0
	v_add_u32_e32 v0, s72, v0
	v_cvt_f32_i32_e32 v1, v0
	v_mul_f32_e32 v1, 0x3b800000, v1
	v_cos_f32_e32 v2, v1
	v_sin_f32_e32 v3, v1
	s_waitcnt lgkmcnt(0)
	s_add_u32 s4, s6, 0x9600000
	s_addc_u32 s5, s7, 0
	s_add_u32 s6, s6, 0xc100000
	s_addc_u32 s7, s7, 0
	v_lshrrev_b32_e32 v4, 7, v0
	v_bfe_u32 v5, v0, 3, 4
	v_and_b32_e32 v6, 7, v0
	v_lshlrev_b32_e32 v7, 7, v6
	v_lshlrev_b32_e32 v8, 11, v4
	v_lshl_add_u32 v8, v5, 3, v8
	v_lshl_add_u32 v9, v4, 4, v5
	v_mul_u32_u24_e32 v9, 0x88, v9
	v_lshl_add_u32 v10, v4, 4, v6
	v_mul_u32_u24_e32 v10, 0x88, v10
	v_lshl_add_u32 v10, v5, 3, v10
	v_mul_u32_u24_e32 v11, v5, v6
	v_lshlrev_b32_e32 v12, 3, v5
	v_add_u32_e32 v12, v11, v12
	v_lshlrev_b32_e32 v11, 3, v11
	v_lshlrev_b32_e32 v12, 3, v12
	v_lshl_add_u32 v13, v6, 4, v5
	v_lshl_add_u32 v13, v4, 8, v13
	v_lshlrev_b32_e32 v13, 3, v13
	v_lshrrev_b32_e32 v14, 1, v0
	v_and_b32_e32 v15, 1, v0
	v_sub_u32_e32 v44, 0x100, v14
	v_and_b32_e32 v44, 0xff, v44
	v_lshlrev_b32_e32 v45, 12, v15
	v_lshl_add_u32 v46, v14, 3, v45
	v_lshl_add_u32 v47, v44, 3, v45
	s_mov_b32 s2, s93
.Lcd_slab:
	s_lshl_b32 s8, s2, 5
	s_and_b32 s8, s8, 0xe0
	s_ashr_i32 s13, s2, 3
	s_add_i32 s8, s8, s13
	s_and_b64 s[14:15], s[10:11], exec
	s_cselect_b32 s8, s8, s2
	s_ashr_i32 s16, s8, 6
	s_and_b32 s8, s8, 63
	s_lshl_b32 s8, s8, 4
	s_lshl_b32 s16, s16, 8
	s_add_i32 s16, s16, 0x4000
	v_cmp_gt_u32_e32 vcc, 0x100, v0
	s_and_saveexec_b64 s[14:15], vcc
	s_cbranch_execz .Lcd_ld_done
	v_add_u32_e32 v48, s16, v0
	v_mul_u32_u24_e32 v48, 0xa00, v48
	v_add_u32_e32 v48, s8, v48
	global_load_dwordx4 v[16:19], v48, s[4:5]
	v_lshlrev_b32_e32 v49, 3, v0
	ds_write_b64 v49, v[2:3] offset:8192
	s_waitcnt vmcnt(0)
	v_lshlrev_b32_e32 v20, 16, v16
	v_and_b32_e32 v21, 0xffff0000, v16
	ds_write_b64 v49, v[20:21]
	v_lshlrev_b32_e32 v20, 16, v17
	v_and_b32_e32 v21, 0xffff0000, v17
	ds_write_b64 v49, v[20:21] offset:2048
	v_lshlrev_b32_e32 v20, 16, v18
	v_and_b32_e32 v21, 0xffff0000, v18
	ds_write_b64 v49, v[20:21] offset:4096
	v_lshlrev_b32_e32 v20, 16, v19
	v_and_b32_e32 v21, 0xffff0000, v19
	ds_write_b64 v49, v[20:21] offset:6144
.Lcd_ld_done:
	s_or_b64 exec, exec, s[14:15]
	s_waitcnt lgkmcnt(0)
	s_barrier
	v_mov_b32_e32 v32, 0
	v_mov_b32_e32 v33, 0
	v_mov_b32_e32 v34, 0
	v_mov_b32_e32 v35, 0
	v_mov_b32_e32 v36, 0
	v_add_u32_e32 v37, v36, v7
	v_and_b32_e32 v37, 0x780, v37
	v_add_u32_e32 v38, v37, v7
	v_and_b32_e32 v38, 0x780, v38
	v_add_u32_e32 v39, v38, v7
	v_and_b32_e32 v39, 0x780, v39
	ds_read_b64 v[16:17], v8
	ds_read_b64 v[24:25], v36 offset:8192
	ds_read_b64 v[18:19], v8 offset:128
	ds_read_b64 v[26:27], v37 offset:8192
	ds_read_b64 v[20:21], v8 offset:256
	ds_read_b64 v[28:29], v38 offset:8192
	ds_read_b64 v[22:23], v8 offset:384
	ds_read_b64 v[30:31], v39 offset:8192
	s_waitcnt lgkmcnt(0)
	v_fma_f32 v32, v16, v24, v32
	v_fma_f32 v33, v17, v24, v33
	v_fma_f32 v32, v17, v25, v32
	v_fma_f32 v33, -v16, v25, v33
	v_fma_f32 v34, v18, v26, v34
	v_fma_f32 v35, v19, v26, v35
	v_fma_f32 v34, v19, v27, v34
	v_fma_f32 v35, -v18, v27, v35
	v_fma_f32 v32, v20, v28, v32
	v_fma_f32 v33, v21, v28, v33
	v_fma_f32 v32, v21, v29, v32
	v_fma_f32 v33, -v20, v29, v33
	v_fma_f32 v34, v22, v30, v34
	v_fma_f32 v35, v23, v30, v35
	v_fma_f32 v34, v23, v31, v34
	v_fma_f32 v35, -v22, v31, v35
	v_add_u32_e32 v36, v39, v7
	v_and_b32_e32 v36, 0x780, v36
	v_add_u32_e32 v37, v36, v7
	v_and_b32_e32 v37, 0x780, v37
	v_add_u32_e32 v38, v37, v7
	v_and_b32_e32 v38, 0x780, v38
	v_add_u32_e32 v39, v38, v7
	v_and_b32_e32 v39, 0x780, v39
	ds_read_b64 v[16:17], v8 offset:512
	ds_read_b64 v[24:25], v36 offset:8192
	ds_read_b64 v[18:19], v8 offset:640
	ds_read_b64 v[26:27], v37 offset:8192
	ds_read_b64 v[20:21], v8 offset:768
	ds_read_b64 v[28:29], v38 offset:8192
	ds_read_b64 v[22:23], v8 offset:896
	ds_read_b64 v[30:31], v39 offset:8192
	s_waitcnt lgkmcnt(0)
	v_fma_f32 v32, v16, v24, v32
	v_fma_f32 v33, v17, v24, v33
	v_fma_f32 v32, v17, v25, v32
	v_fma_f32 v33, -v16, v25, v33
	v_fma_f32 v34, v18, v26, v34
	v_fma_f32 v35, v19, v26, v35
	v_fma_f32 v34, v19, v27, v34
	v_fma_f32 v35, -v18, v27, v35
	v_fma_f32 v32, v20, v28, v32
	v_fma_f32 v33, v21, v28, v33
	v_fma_f32 v32, v21, v29, v32
	v_fma_f32 v33, -v20, v29, v33
	v_fma_f32 v34, v22, v30, v34
	v_fma_f32 v35, v23, v30, v35
	v_fma_f32 v34, v23, v31, v34
	v_fma_f32 v35, -v22, v31, v35
	v_add_u32_e32 v36, v39, v7
	v_and_b32_e32 v36, 0x780, v36
	v_add_u32_e32 v37, v36, v7
	v_and_b32_e32 v37, 0x780, v37
	v_add_u32_e32 v38, v37, v7
	v_and_b32_e32 v38, 0x780, v38
	v_add_u32_e32 v39, v38, v7
	v_and_b32_e32 v39, 0x780, v39
	ds_read_b64 v[16:17], v8 offset:1024
	ds_read_b64 v[24:25], v36 offset:8192
	ds_read_b64 v[18:19], v8 offset:1152
	ds_read_b64 v[26:27], v37 offset:8192
	ds_read_b64 v[20:21], v8 offset:1280
	ds_read_b64 v[28:29], v38 offset:8192
	ds_read_b64 v[22:23], v8 offset:1408
	ds_read_b64 v[30:31], v39 offset:8192
	s_waitcnt lgkmcnt(0)
	v_fma_f32 v32, v16, v24, v32
	v_fma_f32 v33, v17, v24, v33
	v_fma_f32 v32, v17, v25, v32
	v_fma_f32 v33, -v16, v25, v33
	v_fma_f32 v34, v18, v26, v34
	v_fma_f32 v35, v19, v26, v35
	v_fma_f32 v34, v19, v27, v34
	v_fma_f32 v35, -v18, v27, v35
	v_fma_f32 v32, v20, v28, v32
	v_fma_f32 v33, v21, v28, v33
	v_fma_f32 v32, v21, v29, v32
	v_fma_f32 v33, -v20, v29, v33
	v_fma_f32 v34, v22, v30, v34
	v_fma_f32 v35, v23, v30, v35
	v_fma_f32 v34, v23, v31, v34
	v_fma_f32 v35, -v22, v31, v35
	v_add_u32_e32 v36, v39, v7
	v_and_b32_e32 v36, 0x780, v36
	v_add_u32_e32 v37, v36, v7
	v_and_b32_e32 v37, 0x780, v37
	v_add_u32_e32 v38, v37, v7
	v_and_b32_e32 v38, 0x780, v38
	v_add_u32_e32 v39, v38, v7
	v_and_b32_e32 v39, 0x780, v39
	ds_read_b64 v[16:17], v8 offset:1536
	ds_read_b64 v[24:25], v36 offset:8192
	ds_read_b64 v[18:19], v8 offset:1664
	ds_read_b64 v[26:27], v37 offset:8192
	ds_read_b64 v[20:21], v8 offset:1792
	ds_read_b64 v[28:29], v38 offset:8192
	ds_read_b64 v[22:23], v8 offset:1920
	ds_read_b64 v[30:31], v39 offset:8192
	s_waitcnt lgkmcnt(0)
	v_fma_f32 v32, v16, v24, v32
	v_fma_f32 v33, v17, v24, v33
	v_fma_f32 v32, v17, v25, v32
	v_fma_f32 v33, -v16, v25, v33
	v_fma_f32 v34, v18, v26, v34
	v_fma_f32 v35, v19, v26, v35
	v_fma_f32 v34, v19, v27, v34
	v_fma_f32 v35, -v18, v27, v35
	v_fma_f32 v32, v20, v28, v32
	v_fma_f32 v33, v21, v28, v33
	v_fma_f32 v32, v21, v29, v32
	v_fma_f32 v33, -v20, v29, v33
	v_fma_f32 v34, v22, v30, v34
	v_fma_f32 v35, v23, v30, v35
	v_fma_f32 v34, v23, v31, v34
	v_fma_f32 v35, -v22, v31, v35
	v_add_f32_e32 v40, v32, v34
	v_add_f32_e32 v41, v33, v35
	v_sub_f32_e32 v42, v32, v34
	v_sub_f32_e32 v43, v33, v35
	ds_read_b64 v[24:25], v11 offset:8192
	ds_read_b64 v[26:27], v12 offset:8192
	s_waitcnt lgkmcnt(0)
	v_mul_f32_e32 v20, v40, v24
	v_mul_f32_e32 v21, v41, v24
	v_mul_f32_e32 v22, v42, v26
	v_mul_f32_e32 v23, v43, v26
	v_fma_f32 v20, v41, v25, v20
	v_fma_f32 v21, -v40, v25, v21
	v_fma_f32 v22, v43, v27, v22
	v_fma_f32 v23, -v42, v27, v23
	ds_write_b64 v10, v[20:21] offset:12288
	ds_write_b64 v10, v[22:23] offset:13376
	s_waitcnt lgkmcnt(0)
	s_barrier
	v_add_u32_e32 v50, 0x3000, v9
	v_mov_b32_e32 v32, 0
	v_mov_b32_e32 v33, 0
	v_mov_b32_e32 v34, 0
	v_mov_b32_e32 v35, 0
	v_mov_b32_e32 v36, 0
	v_add_u32_e32 v37, v36, v7
	v_and_b32_e32 v37, 0x780, v37
	v_add_u32_e32 v38, v37, v7
	v_and_b32_e32 v38, 0x780, v38
	v_add_u32_e32 v39, v38, v7
	v_and_b32_e32 v39, 0x780, v39
	ds_read_b64 v[16:17], v50
	ds_read_b64 v[24:25], v36 offset:8192
	ds_read_b64 v[18:19], v50 offset:8
	ds_read_b64 v[26:27], v37 offset:8192
	ds_read_b64 v[20:21], v50 offset:16
	ds_read_b64 v[28:29], v38 offset:8192
	ds_read_b64 v[22:23], v50 offset:24
	ds_read_b64 v[30:31], v39 offset:8192
	s_waitcnt lgkmcnt(0)
	v_fma_f32 v32, v16, v24, v32
	v_fma_f32 v33, v17, v24, v33
	v_fma_f32 v32, v17, v25, v32
	v_fma_f32 v33, -v16, v25, v33
	v_fma_f32 v34, v18, v26, v34
	v_fma_f32 v35, v19, v26, v35
	v_fma_f32 v34, v19, v27, v34
	v_fma_f32 v35, -v18, v27, v35
	v_fma_f32 v32, v20, v28, v32
	v_fma_f32 v33, v21, v28, v33
	v_fma_f32 v32, v21, v29, v32
	v_fma_f32 v33, -v20, v29, v33
	v_fma_f32 v34, v22, v30, v34
	v_fma_f32 v35, v23, v30, v35
	v_fma_f32 v34, v23, v31, v34
	v_fma_f32 v35, -v22, v31, v35
	v_add_u32_e32 v36, v39, v7
	v_and_b32_e32 v36, 0x780, v36
	v_add_u32_e32 v37, v36, v7
	v_and_b32_e32 v37, 0x780, v37
	v_add_u32_e32 v38, v37, v7
	v_and_b32_e32 v38, 0x780, v38
	v_add_u32_e32 v39, v38, v7
	v_and_b32_e32 v39, 0x780, v39
	ds_read_b64 v[16:17], v50 offset:32
	ds_read_b64 v[24:25], v36 offset:8192
	ds_read_b64 v[18:19], v50 offset:40
	ds_read_b64 v[26:27], v37 offset:8192
	ds_read_b64 v[20:21], v50 offset:48
	ds_read_b64 v[28:29], v38 offset:8192
	ds_read_b64 v[22:23], v50 offset:56
	ds_read_b64 v[30:31], v39 offset:8192
	s_waitcnt lgkmcnt(0)
	v_fma_f32 v32, v16, v24, v32
	v_fma_f32 v33, v17, v24, v33
	v_fma_f32 v32, v17, v25, v32
	v_fma_f32 v33, -v16, v25, v33
	v_fma_f32 v34, v18, v26, v34
	v_fma_f32 v35, v19, v26, v35
	v_fma_f32 v34, v19, v27, v34
	v_fma_f32 v35, -v18, v27, v35
	v_fma_f32 v32, v20, v28, v32
	v_fma_f32 v33, v21, v28, v33
	v_fma_f32 v32, v21, v29, v32
	v_fma_f32 v33, -v20, v29, v33
	v_fma_f32 v34, v22, v30, v34
	v_fma_f32 v35, v23, v30, v35
	v_fma_f32 v34, v23, v31, v34
	v_fma_f32 v35, -v22, v31, v35
	v_add_u32_e32 v36, v39, v7
	v_and_b32_e32 v36, 0x780, v36
	v_add_u32_e32 v37, v36, v7
	v_and_b32_e32 v37, 0x780, v37
	v_add_u32_e32 v38, v37, v7
	v_and_b32_e32 v38, 0x780, v38
	v_add_u32_e32 v39, v38, v7
	v_and_b32_e32 v39, 0x780, v39
	ds_read_b64 v[16:17], v50 offset:64
	ds_read_b64 v[24:25], v36 offset:8192
	ds_read_b64 v[18:19], v50 offset:72
	ds_read_b64 v[26:27], v37 offset:8192
	ds_read_b64 v[20:21], v50 offset:80
	ds_read_b64 v[28:29], v38 offset:8192
	ds_read_b64 v[22:23], v50 offset:88
	ds_read_b64 v[30:31], v39 offset:8192
	s_waitcnt lgkmcnt(0)
	v_fma_f32 v32, v16, v24, v32
	v_fma_f32 v33, v17, v24, v33
	v_fma_f32 v32, v17, v25, v32
	v_fma_f32 v33, -v16, v25, v33
	v_fma_f32 v34, v18, v26, v34
	v_fma_f32 v35, v19, v26, v35
	v_fma_f32 v34, v19, v27, v34
	v_fma_f32 v35, -v18, v27, v35
	v_fma_f32 v32, v20, v28, v32
	v_fma_f32 v33, v21, v28, v33
	v_fma_f32 v32, v21, v29, v32
	v_fma_f32 v33, -v20, v29, v33
	v_fma_f32 v34, v22, v30, v34
	v_fma_f32 v35, v23, v30, v35
	v_fma_f32 v34, v23, v31, v34
	v_fma_f32 v35, -v22, v31, v35
	v_add_u32_e32 v36, v39, v7
	v_and_b32_e32 v36, 0x780, v36
	v_add_u32_e32 v37, v36, v7
	v_and_b32_e32 v37, 0x780, v37
	v_add_u32_e32 v38, v37, v7
	v_and_b32_e32 v38, 0x780, v38
	v_add_u32_e32 v39, v38, v7
	v_and_b32_e32 v39, 0x780, v39
	ds_read_b64 v[16:17], v50 offset:96
	ds_read_b64 v[24:25], v36 offset:8192
	ds_read_b64 v[18:19], v50 offset:104
	ds_read_b64 v[26:27], v37 offset:8192
	ds_read_b64 v[20:21], v50 offset:112
	ds_read_b64 v[28:29], v38 offset:8192
	ds_read_b64 v[22:23], v50 offset:120
	ds_read_b64 v[30:31], v39 offset:8192
	s_waitcnt lgkmcnt(0)
	v_fma_f32 v32, v16, v24, v32
	v_fma_f32 v33, v17, v24, v33
	v_fma_f32 v32, v17, v25, v32
	v_fma_f32 v33, -v16, v25, v33
	v_fma_f32 v34, v18, v26, v34
	v_fma_f32 v35, v19, v26, v35
	v_fma_f32 v34, v19, v27, v34
	v_fma_f32 v35, -v18, v27, v35
	v_fma_f32 v32, v20, v28, v32
	v_fma_f32 v33, v21, v28, v33
	v_fma_f32 v32, v21, v29, v32
	v_fma_f32 v33, -v20, v29, v33
	v_fma_f32 v34, v22, v30, v34
	v_fma_f32 v35, v23, v30, v35
	v_fma_f32 v34, v23, v31, v34
	v_fma_f32 v35, -v22, v31, v35
	v_add_f32_e32 v40, v32, v34
	v_add_f32_e32 v41, v33, v35
	v_sub_f32_e32 v42, v32, v34
	v_sub_f32_e32 v43, v33, v35
	ds_write_b64 v13, v[40:41] offset:24576
	ds_write_b64 v13, v[42:43] offset:25600
	s_waitcnt lgkmcnt(0)
	s_barrier
	ds_read_b64 v[16:17], v46 offset:24576
	ds_read_b64 v[18:19], v47 offset:24576
	ds_read_b64 v[20:21], v46 offset:26624
	ds_read_b64 v[22:23], v47 offset:26624
	v_add_u32_e32 v48, s16, v14
	v_mul_u32_u24_e32 v48, 0xc00, v48
	v_add_u32_e32 v48, s8, v48
	v_lshl_add_u32 v48, v15, 3, v48
	s_waitcnt lgkmcnt(0)
	v_add_f32_e32 v24, v16, v18
	v_add_f32_e32 v25, v17, v19
	v_sub_f32_e32 v26, v17, v19
	v_sub_f32_e32 v27, v18, v16
	v_add_f32_e32 v28, v20, v22
	v_add_f32_e32 v29, v21, v23
	v_sub_f32_e32 v30, v21, v23
	v_sub_f32_e32 v31, v22, v20
	v_mul_f32_e32 v24, 0x3d000000, v24
	v_mul_f32_e32 v25, 0x3d000000, v25
	v_mul_f32_e32 v26, 0x3d000000, v26
	v_mul_f32_e32 v27, 0x3d000000, v27
	v_mul_f32_e32 v28, 0x3d000000, v28
	v_mul_f32_e32 v29, 0x3d000000, v29
	v_mul_f32_e32 v30, 0x3d000000, v30
	v_mul_f32_e32 v31, 0x3d000000, v31
	s_nop 0
	v_cvt_pk_bf16_f32 v32, v24, v25
	v_cvt_pk_bf16_f32 v33, v28, v29
	v_cvt_pk_bf16_f32 v34, v26, v27
	v_cvt_pk_bf16_f32 v35, v30, v31
	global_store_dwordx2 v48, v[32:33], s[6:7]
	global_store_dwordx2 v48, v[34:35], s[6:7] offset:1024
	s_add_i32 s2, s2, s74
	s_cmpk_gt_i32 s2, 0xff
	s_barrier
	s_cbranch_scc0 .Lcd_slab
